# phase 0->1 seam: cooperative-groups grid sync replaced by the in-kernel XCD barrier behind a zeroed-words ready flag; census loads issued back to back
# speedup vs baseline: 1.0161x; 1.0161x over previous
.LBB0_5:
	v_add_co_u32_e32 v1, vcc, 0x200, v1
	s_xor_b64 s[2:3], vcc, -1
	s_and_b64 s[2:3], exec, s[2:3]
	global_store_dwordx4 v[6:7], v[2:5], off
	s_or_b64 s[4:5], s[2:3], s[4:5]
	v_lshl_add_u64 v[6:7], v[6:7], 0, s[6:7]
	s_andn2_b64 exec, exec, s[4:5]
	s_cbranch_execnz .LBB0_5
	s_or_b64 exec, exec, s[4:5]
	s_waitcnt vmcnt(0)
	s_barrier
	v_and_b32_e32 v1, 0x3ff, v0
	v_cmp_eq_u32_e32 vcc, 0, v1
	s_and_saveexec_b64 s[8:9], vcc
	s_cbranch_execz .Lp0_flag_set
	buffer_wbl2 sc1
	s_waitcnt vmcnt(0)
	s_load_dwordx4 s[4:7], s[0:1], 0x80
	s_waitcnt lgkmcnt(0)
	s_add_u32 s6, s6, 0x13ef4800
	s_addc_u32 s7, s7, 0
	v_mov_b32_e32 v1, 0
	v_mov_b32_e32 v2, 0x600df1a6
	global_store_dword v1, v2, s[6:7] sc0 sc1
	s_waitcnt vmcnt(0)
.Lp0_flag_set:
	s_or_b64 exec, exec, s[8:9]
.LBB0_7:
	s_waitcnt lgkmcnt(0)
	s_barrier

.Lxcd_entry:
	s_waitcnt vmcnt(0)
	s_waitcnt lgkmcnt(0)
	s_barrier
	s_mov_b64 s[0:1], exec
	v_readlane_b32 s4, v253, 49
	v_readlane_b32 s5, v253, 50
	s_and_b64 s[4:5], s[0:1], s[4:5]
	s_mov_b64 exec, s[4:5]
	s_cbranch_execz .LBB0_855
	v_readlane_b32 s4, v253, 46
	s_waitcnt vmcnt(0) expcnt(0) lgkmcnt(0)
	s_nop 0
	v_mov_b32_e32 v0, s4
	ds_read_b32 v2, v0
	v_readlane_b32 s4, v253, 47
	s_waitcnt lgkmcnt(0)
	v_cmp_ne_u32_e32 vcc, 0, v2
	v_mov_b32_e32 v0, s4
	ds_read_b32 v0, v0
	s_cbranch_vccnz .LBB0_823
	v_readlane_b32 s6, v252, 7
	v_readlane_b32 s7, v252, 8
	s_load_dwordx2 s[4:5], s[6:7], 0x0
	s_nop 0
	s_load_dword s6, s[6:7], 0x8
	s_mov_b32 s11, 1
	s_waitcnt lgkmcnt(0)
	s_mul_i32 s10, s5, s4
	s_mul_i32 s10, s10, s6
	s_branch .LBB0_811

.LBB0_811:
	v_readlane_b32 s4, v252, 41
	v_readlane_b32 s5, v252, 42
	s_mov_b64 s[6:7], -1
	s_nop 3
	global_load_dword v0, v3, s[4:5] sc1
	v_readlane_b32 s4, v252, 43
	v_readlane_b32 s5, v252, 44
	s_nop 4
	global_load_dword v1, v3, s[4:5] sc1
	v_readlane_b32 s4, v252, 45
	v_readlane_b32 s5, v252, 46
	s_nop 1
	s_nop 2
	global_load_dword v2, v3, s[4:5] sc1
	v_readlane_b32 s4, v252, 47
	v_readlane_b32 s5, v252, 48
	s_nop 1
	s_nop 2
	global_load_dword v4, v3, s[4:5] sc1
	v_readlane_b32 s4, v252, 49
	v_readlane_b32 s5, v252, 50
	s_nop 1
	s_nop 2
	global_load_dword v5, v3, s[4:5] sc1
	v_readlane_b32 s4, v252, 51
	v_readlane_b32 s5, v252, 52
	s_nop 1
	s_nop 2
	global_load_dword v6, v3, s[4:5] sc1
	v_readlane_b32 s4, v252, 53
	v_readlane_b32 s5, v252, 54
	s_nop 1
	s_nop 2
	global_load_dword v7, v3, s[4:5] sc1
	v_readlane_b32 s4, v252, 55
	v_readlane_b32 s5, v252, 56
	s_nop 1
	s_nop 2
	global_load_dword v8, v3, s[4:5] sc1
	v_readlane_b32 s4, v252, 57
	v_readlane_b32 s5, v252, 58
	s_nop 1
	s_nop 2
	global_load_dword v9, v3, s[4:5] sc1
	v_readlane_b32 s4, v252, 59
	v_readlane_b32 s5, v252, 60
	s_nop 1
	s_nop 2
	global_load_dword v10, v3, s[4:5] sc1
	v_readlane_b32 s4, v252, 61
	v_readlane_b32 s5, v252, 62
	s_nop 1
	s_nop 2
	global_load_dword v11, v3, s[4:5] sc1
	v_readlane_b32 s4, v252, 63
	v_readlane_b32 s5, v253, 0
	s_nop 1
	s_nop 2
	global_load_dword v12, v3, s[4:5] sc1
	v_readlane_b32 s4, v253, 1
	v_readlane_b32 s5, v253, 2
	s_nop 1
	s_nop 2
	global_load_dword v13, v3, s[4:5] sc1
	v_readlane_b32 s4, v253, 3
	v_readlane_b32 s5, v253, 4
	s_nop 1
	s_nop 2
	global_load_dword v14, v3, s[4:5] sc1
	v_readlane_b32 s4, v253, 5
	v_readlane_b32 s5, v253, 6
	s_nop 1
	s_nop 2
	global_load_dword v15, v3, s[4:5] sc1
	v_readlane_b32 s4, v253, 7
	v_readlane_b32 s5, v253, 8
	s_nop 1
	s_nop 2
	global_load_dword v16, v3, s[4:5] sc1
	s_mov_b64 s[4:5], -1
	s_waitcnt vmcnt(0)
	v_add_u32_e32 v17, v1, v0
	v_add_u32_e32 v17, v17, v2
	v_add_u32_e32 v17, v17, v4
	v_add_u32_e32 v17, v17, v5
	v_add_u32_e32 v17, v17, v6
	v_add_u32_e32 v17, v17, v7
	v_add_u32_e32 v17, v17, v8
	v_add_u32_e32 v17, v17, v9
	v_add_u32_e32 v17, v17, v10
	v_add_u32_e32 v17, v17, v11
	v_add_u32_e32 v17, v17, v12
	v_add_u32_e32 v17, v17, v13
	v_add_u32_e32 v17, v17, v14
	v_add_u32_e32 v17, v17, v15
	v_add_u32_e32 v17, v17, v16
	v_cmp_eq_u32_e32 vcc, s10, v17
	s_cbranch_vccnz .LBB0_810
	s_and_b32 s4, s11, 0xff
	s_cmp_eq_u32 s4, 0
	s_mov_b64 s[4:5], -1
	s_mov_b64 s[8:9], -1
	s_sleep 1
	s_cbranch_scc1 .LBB0_815
	s_and_b64 vcc, exec, s[8:9]
	s_cbranch_vccz .LBB0_810

.LBB0_856:
	s_branch .LBB0_12
.Lp0_sync:
	s_waitcnt vmcnt(0)
	s_waitcnt lgkmcnt(0)
	s_barrier
	s_getreg_b32 s0, hwreg(HW_REG_XCC_ID, 0, 4)
	s_and_b32 s0, s0, 15
	v_writelane_b32 v253, s0, 48
	s_mov_b64 s[0:1], exec
	v_readlane_b32 s4, v253, 49
	v_readlane_b32 s5, v253, 50
	s_and_b64 s[4:5], s[0:1], s[4:5]
	s_mov_b64 exec, s[4:5]
	s_cbranch_execz .Lp0_posted
	v_readlane_b32 s6, v252, 4
	v_readlane_b32 s7, v252, 5
	s_mov_b32 s8, 0
	s_nop 3
	s_add_u32 s10, s6, 0x3c00
	s_addc_u32 s11, s7, 0
.Lp0_poll:
	global_load_dword v0, v3, s[10:11] sc1
	s_waitcnt vmcnt(0)
	v_cmp_eq_u32_e32 vcc, 0x600df1a6, v0
	s_cbranch_vccnz .Lp0_flag_ok
	s_sleep 2
	s_add_i32 s8, s8, 1
	s_cmp_lt_u32 s8, 0x8000
	s_cbranch_scc1 .Lp0_poll
.Lp0_flag_ok:
	v_readlane_b32 s8, v253, 48
	s_nop 3
	s_lshl_b32 s8, s8, 8
	v_mov_b32_e32 v0, s8
	v_mov_b32_e32 v1, 1
	global_atomic_add v0, v1, s[6:7] offset:1024
.Lp0_posted:
	s_mov_b64 exec, s[0:1]
	s_branch .Lxcd_entry
